# sel/MoBA loops: 4-slot LDS ring so the K/V DMA of pair i+2 is issued before the interval's barrier (off the post-barrier critical path)
# speedup vs baseline: 1.0099x; 1.0021x over previous
; #define MFMA32(a, b, c) __builtin_amdgcn_mfma_f32_32x32x16_bf16((a), (b), (c), 0, 0, 0)
; template <class KP, class VP, class ACT, class FILL>
; DI void attn_loop(AttnSt& st, const bf16x8 (&qf)[4], int k0, int k1, size_t vstride, KP kp, VP vp, ACT act, FILL fill) {
;     ...
;   for (int kt = k0; kt <= k1; ++kt) {
;     const int kn = (kt < k1) ? kt + 1 : k1;
;     const int kn2 = (kt + 2 <= k1) ? kt + 2 : k1;
;     {
;       const bf16_t* v0 = vp(kn);
; #pragma unroll
;       for (int j = 0; j < 8; ++j) nxt.v[j] = *(const s16x4*)(v0 + 256 * j);
;     }
;     bf16x8 k2[4];
;     {
;       const bf16_t* krow = kp(kn2);
; #pragma unroll
;       for (int ss = 0; ss < 4; ++ss) k2[ss] = *(const bf16x8*)(krow + 512 * ss);
;     }
;     f32x16 s_next;
; #pragma unroll
;     for (int i = 0; i < 16; ++i) s_next[i] = 0.f;
; #pragma unroll
;     for (int ss = 0; ss < 4; ++ss) s_next = MFMA32(nxt.k[ss], qf[ss], s_next);
; DI void nsa_main_item(const Params& p, int b, int head, int qb, const unsigned char* blut, const float* tbl) {
;     ...
;     attn_loop(st, qf, 0, qb, 32,
;       [&](int kt) { return K + (size_t)kt * 2048 + (h * 32 + r) * 8; },
;       [&](int kt) { return Vt + (size_t)kt * 2048 + (h * 32 + r) * 4; },
;       [&](int kt) { return __ballot((selm >> (kt >> 1)) & 1ull) != 0ull; },
;       [&](int kt, const f32x16& s, float (&lg)[16]) {
;         const bool bs = (selm >> (kt >> 1)) & 1ull;
.Lasel_loop:
	s_lshr_b32 s23, s56, 1
	s_add_u32 s23, s23, 2
	s_add_u32 s61, s100, 0x8000
	s_sub_u32 s24, s61, 0x10000
	s_cmp_ge_u32 s61, 0x20000
	s_cselect_b32 s61, s24, s61
	s_lshr_b32 s24, s59, 1
	s_min_u32 s24, s23, s24
	s_lshl_b32 s26, s24, 13
	s_lshl_b32 s24, s58, 10
	s_add_u32 s26, s26, s24
	s_mov_b32 s27, 0
	v_lshl_add_u64 v[248:249], v[148:149], 0, s[26:27]
	v_lshl_add_u64 v[250:251], v[170:171], 0, s[26:27]
	v_add_co_u32_e32 v250, vcc, v250, v247
	v_addc_co_u32_e32 v251, vcc, 0, v251, vcc
	s_add_u32 s24, s24, s61
	s_mov_b32 m0, s24
	s_nop 0
	global_load_lds_dwordx4 v[248:249], off
	s_add_u32 s24, s24, 0x2000
	s_mov_b32 m0, s24
	s_nop 0
	global_load_lds_dwordx4 v[250:251], off
	s_waitcnt vmcnt(4)
	s_barrier
	s_cmp_le_u32 s56, s60
	s_cbranch_scc0 .Lasel_skip
	v_lshl_add_u32 v248, v247, 1, s100
	ds_read_b128 v[96:99], v248 offset:0
	ds_read_b128 v[112:115], v248 offset:4096
	ds_read_b128 v[100:103], v248 offset:1024
	ds_read_b128 v[116:119], v248 offset:5120
	ds_read_b128 v[104:107], v248 offset:2048
	ds_read_b128 v[120:123], v248 offset:6144
	ds_read_b128 v[108:111], v248 offset:3072
	ds_read_b128 v[124:127], v248 offset:7168
	s_sub_i32 s61, s60, s56
	s_lshr_b32 s23, s56, 1
	v_lshrrev_b64 v[248:249], s23, v[168:169]
	v_and_b32_e32 v248, 1, v248
	v_cmp_eq_u32_e64 s[62:63], 1, v248
	s_waitcnt lgkmcnt(6)
	v_mfma_f32_32x32x16_bf16 v[32:47], v[96:99], v[80:83], 0
	v_mfma_f32_32x32x16_bf16 v[48:63], v[112:115], v[80:83], 0
	s_waitcnt lgkmcnt(4)
	v_mfma_f32_32x32x16_bf16 v[32:47], v[100:103], v[84:87], v[32:47]
	v_mfma_f32_32x32x16_bf16 v[48:63], v[116:119], v[84:87], v[48:63]
	s_waitcnt lgkmcnt(2)
	v_mfma_f32_32x32x16_bf16 v[32:47], v[104:107], v[88:91], v[32:47]
	v_mfma_f32_32x32x16_bf16 v[48:63], v[120:123], v[88:91], v[48:63]
	s_waitcnt lgkmcnt(0)
	v_mfma_f32_32x32x16_bf16 v[32:47], v[108:111], v[92:95], v[32:47]
	v_mfma_f32_32x32x16_bf16 v[48:63], v[124:127], v[92:95], v[48:63]
	v_add_u32_e32 v250, s100, v247
	ds_read_b64 v[64:65], v250 offset:8192
	ds_read_b64 v[66:67], v250 offset:8704
	ds_read_b64 v[68:69], v250 offset:9216
	ds_read_b64 v[70:71], v250 offset:9728
	ds_read_b64 v[72:73], v250 offset:10240
	ds_read_b64 v[74:75], v250 offset:10752
	ds_read_b64 v[76:77], v250 offset:11264
	ds_read_b64 v[78:79], v250 offset:11776
	ds_read_b64 v[172:173], v250 offset:12288
	ds_read_b64 v[174:175], v250 offset:12800
	ds_read_b64 v[176:177], v250 offset:13312
	ds_read_b64 v[178:179], v250 offset:13824
	ds_read_b64 v[180:181], v250 offset:14336
	ds_read_b64 v[182:183], v250 offset:14848
	ds_read_b64 v[184:185], v250 offset:15360
	ds_read_b64 v[186:187], v250 offset:15872
	s_cmp_ge_i32 s61, 50
	s_cbranch_scc1 .Lasel_far
; #define NEGINF (-__builtin_inff())
; DI int crow(int i, int h) { return (i & 3) + 8 * (i >> 2) + 4 * h; }
; DI void nsa_main_item(const Params& p, int b, int head, int qb, const unsigned char* blut, const float* tbl) {
;     ...
;           int dist[16]; float bv[16];
; #pragma unroll
;           for (int i = 0; i < 16; ++i) dist[i] = t - (kt * 32 + crow(i, h));
;           bias16(blut, tblh, dist, bv);
; #pragma unroll
;           for (int i = 0; i < 16; ++i) lg[i] = (bs && dist[i] >= 0) ? s[i] + bv[i] : NEGINF;
	s_lshl_b32 s23, s61, 5
	v_add_u32_e32 v241, s23, v221
	v_lshl_add_u32 v244, v241, 2, v242
	v_subrev_u32_e32 v245, 128, v244
	ds_read_b32 v224, v244 offset:108
	ds_read_b32 v225, v244 offset:104
	ds_read_b32 v226, v244 offset:100
	ds_read_b32 v227, v244 offset:96
	ds_read_b32 v228, v244 offset:76
	ds_read_b32 v229, v244 offset:72
	ds_read_b32 v230, v244 offset:68
	ds_read_b32 v231, v244 offset:64
	ds_read_b32 v232, v244 offset:44
	ds_read_b32 v233, v244 offset:40
	ds_read_b32 v234, v244 offset:36
	ds_read_b32 v235, v244 offset:32
	ds_read_b32 v236, v244 offset:12
	ds_read_b32 v237, v244 offset:8
	ds_read_b32 v238, v244 offset:4
	ds_read_b32 v239, v244 offset:0
	s_waitcnt lgkmcnt(8)
	v_add_f32_e32 v32, v32, v224
	v_add_f32_e32 v33, v33, v225
	v_add_f32_e32 v34, v34, v226
	v_add_f32_e32 v35, v35, v227
	v_add_f32_e32 v36, v36, v228
	v_add_f32_e32 v37, v37, v229
	v_add_f32_e32 v38, v38, v230
	v_add_f32_e32 v39, v39, v231
	s_waitcnt lgkmcnt(0)
	v_add_f32_e32 v40, v40, v232
	v_add_f32_e32 v41, v41, v233
	v_add_f32_e32 v42, v42, v234
	v_add_f32_e32 v43, v43, v235
	v_add_f32_e32 v44, v44, v236
	v_add_f32_e32 v45, v45, v237
	v_add_f32_e32 v46, v46, v238
	v_add_f32_e32 v47, v47, v239
	ds_read_b32 v224, v245 offset:108
	ds_read_b32 v225, v245 offset:104
	ds_read_b32 v226, v245 offset:100
	ds_read_b32 v227, v245 offset:96
	ds_read_b32 v228, v245 offset:76
	ds_read_b32 v229, v245 offset:72
	ds_read_b32 v230, v245 offset:68
	ds_read_b32 v231, v245 offset:64
	ds_read_b32 v232, v245 offset:44
	ds_read_b32 v233, v245 offset:40
	ds_read_b32 v234, v245 offset:36
	ds_read_b32 v235, v245 offset:32
	ds_read_b32 v236, v245 offset:12
	ds_read_b32 v237, v245 offset:8
	ds_read_b32 v238, v245 offset:4
	ds_read_b32 v239, v245 offset:0
	s_waitcnt lgkmcnt(8)
	v_add_f32_e32 v48, v48, v224
	v_add_f32_e32 v49, v49, v225
	v_add_f32_e32 v50, v50, v226
	v_add_f32_e32 v51, v51, v227
	v_add_f32_e32 v52, v52, v228
	v_add_f32_e32 v53, v53, v229
	v_add_f32_e32 v54, v54, v230
	v_add_f32_e32 v55, v55, v231
	s_waitcnt lgkmcnt(0)
	v_add_f32_e32 v56, v56, v232
	v_add_f32_e32 v57, v57, v233
	v_add_f32_e32 v58, v58, v234
	v_add_f32_e32 v59, v59, v235
	v_add_f32_e32 v60, v60, v236
	v_add_f32_e32 v61, v61, v237
	v_add_f32_e32 v62, v62, v238
	v_add_f32_e32 v63, v63, v239
	s_cmp_ge_i32 s61, 2
	s_cbranch_scc1 .Lasel_sm0
	v_subrev_u32_e32 v246, 32, v241
	v_cmp_le_i32_e32 vcc, 0, v241
	s_nop 1
	v_cndmask_b32_e32 v32, v199, v32, vcc
	v_cmp_le_i32_e32 vcc, 1, v241
	s_nop 1
	v_cndmask_b32_e32 v33, v199, v33, vcc
	v_cmp_le_i32_e32 vcc, 2, v241
	s_nop 1
	v_cndmask_b32_e32 v34, v199, v34, vcc
	v_cmp_le_i32_e32 vcc, 3, v241
	s_nop 1
	v_cndmask_b32_e32 v35, v199, v35, vcc
	v_cmp_le_i32_e32 vcc, 8, v241
	s_nop 1
	v_cndmask_b32_e32 v36, v199, v36, vcc
	v_cmp_le_i32_e32 vcc, 9, v241
	s_nop 1
	v_cndmask_b32_e32 v37, v199, v37, vcc
	v_cmp_le_i32_e32 vcc, 10, v241
	s_nop 1
	v_cndmask_b32_e32 v38, v199, v38, vcc
	v_cmp_le_i32_e32 vcc, 11, v241
	s_nop 1
	v_cndmask_b32_e32 v39, v199, v39, vcc
	v_cmp_le_i32_e32 vcc, 16, v241
	s_nop 1
	v_cndmask_b32_e32 v40, v199, v40, vcc
	v_cmp_le_i32_e32 vcc, 17, v241
	s_nop 1
	v_cndmask_b32_e32 v41, v199, v41, vcc
	v_cmp_le_i32_e32 vcc, 18, v241
	s_nop 1
	v_cndmask_b32_e32 v42, v199, v42, vcc
	v_cmp_le_i32_e32 vcc, 19, v241
	s_nop 1
	v_cndmask_b32_e32 v43, v199, v43, vcc
	v_cmp_le_i32_e32 vcc, 24, v241
	s_nop 1
	v_cndmask_b32_e32 v44, v199, v44, vcc
	v_cmp_le_i32_e32 vcc, 25, v241
	s_nop 1
	v_cndmask_b32_e32 v45, v199, v45, vcc
	v_cmp_le_i32_e32 vcc, 26, v241
	s_nop 1
	v_cndmask_b32_e32 v46, v199, v46, vcc
	v_cmp_le_i32_e32 vcc, 27, v241
	s_nop 1
	v_cndmask_b32_e32 v47, v199, v47, vcc
	v_cmp_le_i32_e32 vcc, 0, v246
	s_nop 1
	v_cndmask_b32_e32 v48, v199, v48, vcc
	v_cmp_le_i32_e32 vcc, 1, v246
	s_nop 1
	v_cndmask_b32_e32 v49, v199, v49, vcc
	v_cmp_le_i32_e32 vcc, 2, v246
	s_nop 1
	v_cndmask_b32_e32 v50, v199, v50, vcc
	v_cmp_le_i32_e32 vcc, 3, v246
	s_nop 1
	v_cndmask_b32_e32 v51, v199, v51, vcc
	v_cmp_le_i32_e32 vcc, 8, v246
	s_nop 1
	v_cndmask_b32_e32 v52, v199, v52, vcc
	v_cmp_le_i32_e32 vcc, 9, v246
	s_nop 1
	v_cndmask_b32_e32 v53, v199, v53, vcc
	v_cmp_le_i32_e32 vcc, 10, v246
	s_nop 1
	v_cndmask_b32_e32 v54, v199, v54, vcc
	v_cmp_le_i32_e32 vcc, 11, v246
	s_nop 1
	v_cndmask_b32_e32 v55, v199, v55, vcc
	v_cmp_le_i32_e32 vcc, 16, v246
	s_nop 1
	v_cndmask_b32_e32 v56, v199, v56, vcc
	v_cmp_le_i32_e32 vcc, 17, v246
	s_nop 1
	v_cndmask_b32_e32 v57, v199, v57, vcc
	v_cmp_le_i32_e32 vcc, 18, v246
	s_nop 1
	v_cndmask_b32_e32 v58, v199, v58, vcc
	v_cmp_le_i32_e32 vcc, 19, v246
	s_nop 1
	v_cndmask_b32_e32 v59, v199, v59, vcc
	v_cmp_le_i32_e32 vcc, 24, v246
	s_nop 1
	v_cndmask_b32_e32 v60, v199, v60, vcc
	v_cmp_le_i32_e32 vcc, 25, v246
	s_nop 1
	v_cndmask_b32_e32 v61, v199, v61, vcc
	v_cmp_le_i32_e32 vcc, 26, v246
	s_nop 1
	v_cndmask_b32_e32 v62, v199, v62, vcc
	v_cmp_le_i32_e32 vcc, 27, v246
	s_nop 1
	v_cndmask_b32_e32 v63, v199, v63, vcc

; template <class KP, class VP, class ACT, class FILL>
; DI void attn_loop(AttnSt& st, const bf16x8 (&qf)[4], int k0, int k1, size_t vstride, KP kp, VP vp, ACT act, FILL fill) {
;     ...
;   for (int kt = k0; kt <= k1; ++kt) {
.Lasel_skip:
	s_add_u32 s100, s100, 0x4000
	s_cmp_eq_u32 s100, 0x20000
	s_cselect_b32 s100, 0x10000, s100
	s_add_u32 s56, s56, 2
	s_cmp_le_u32 s56, s59
	s_cbranch_scc1 .Lasel_loop
	s_nop 15
	s_waitcnt vmcnt(0)
	s_mov_b64 s[58:59], 0
	s_branch .LBB0_701

; #define MFMA32(a, b, c) __builtin_amdgcn_mfma_f32_32x32x16_bf16((a), (b), (c), 0, 0, 0)
; template <class KP, class VP, class ACT, class FILL>
; DI void attn_loop(AttnSt& st, const bf16x8 (&qf)[4], int k0, int k1, size_t vstride, KP kp, VP vp, ACT act, FILL fill) {
;     ...
;   for (int kt = k0; kt <= k1; ++kt) {
;     const int kn = (kt < k1) ? kt + 1 : k1;
;     const int kn2 = (kt + 2 <= k1) ? kt + 2 : k1;
;     {
;       const bf16_t* v0 = vp(kn);
; #pragma unroll
;       for (int j = 0; j < 8; ++j) nxt.v[j] = *(const s16x4*)(v0 + 256 * j);
;     }
;     bf16x8 k2[4];
;     {
;       const bf16_t* krow = kp(kn2);
; #pragma unroll
;       for (int ss = 0; ss < 4; ++ss) k2[ss] = *(const bf16x8*)(krow + 512 * ss);
;     }
;     f32x16 s_next;
; #pragma unroll
;     for (int i = 0; i < 16; ++i) s_next[i] = 0.f;
; #pragma unroll
;     for (int ss = 0; ss < 4; ++ss) s_next = MFMA32(nxt.k[ss], qf[ss], s_next);
; DI void moba_item(const Params& p, int b, int hd, int qb, const unsigned char* blut, const float* tbl) {
;     ...
;   attn_loop(st, qf, 0, qb, 32,
;     [&](int kt) { return K + (size_t)kt * 2048 + (h * 32 + r) * 8; },
;     [&](int kt) { return Vt + (size_t)kt * 2048 + (h * 32 + r) * 4; },
;     [&](int kt) { return __ballot((mmask >> (kt >> 3)) & 1u) != 0ull; },
;     [&](int kt, const f32x16& s, float (&lg)[16]) {
.Lamoba_loop:
	s_lshr_b32 s23, s56, 1
	s_add_u32 s23, s23, 2
	s_add_u32 s61, s100, 0x8000
	s_sub_u32 s24, s61, 0x10000
	s_cmp_ge_u32 s61, 0x20000
	s_cselect_b32 s61, s24, s61
	s_lshr_b32 s24, s59, 1
	s_min_u32 s24, s23, s24
	s_lshl_b32 s26, s24, 13
	s_lshl_b32 s24, s58, 10
	s_add_u32 s26, s26, s24
	s_mov_b32 s27, 0
	v_lshl_add_u64 v[186:187], v[134:135], 0, s[26:27]
	v_lshl_add_u64 v[218:219], v[136:137], 0, s[26:27]
	v_add_co_u32_e32 v218, vcc, v218, v185
	v_addc_co_u32_e32 v219, vcc, 0, v219, vcc
	s_add_u32 s24, s24, s61
	s_mov_b32 m0, s24
	s_nop 0
	global_load_lds_dwordx4 v[186:187], off
	s_add_u32 s24, s24, 0x2000
	s_mov_b32 m0, s24
	s_nop 0
	global_load_lds_dwordx4 v[218:219], off
	s_waitcnt vmcnt(4)
	s_barrier
	s_cmp_le_u32 s56, s60
	s_cbranch_scc0 .Lamoba_skip
	v_lshl_add_u32 v186, v185, 1, s100
	ds_read_b128 v[96:99], v186 offset:0
	ds_read_b128 v[112:115], v186 offset:4096
	ds_read_b128 v[100:103], v186 offset:1024
	ds_read_b128 v[116:119], v186 offset:5120
	ds_read_b128 v[104:107], v186 offset:2048
	ds_read_b128 v[120:123], v186 offset:6144
	ds_read_b128 v[108:111], v186 offset:3072
	ds_read_b128 v[124:127], v186 offset:7168
	s_sub_i32 s61, s60, s56
	s_lshr_b32 s23, s56, 3
	v_bfe_u32 v184, v157, s23, 1
	v_cmp_eq_u32_e64 s[62:63], 1, v184
	s_waitcnt lgkmcnt(6)
	v_mfma_f32_32x32x16_bf16 v[32:47], v[96:99], v[80:83], 0
	v_mfma_f32_32x32x16_bf16 v[48:63], v[112:115], v[80:83], 0
	s_waitcnt lgkmcnt(4)
	v_mfma_f32_32x32x16_bf16 v[32:47], v[100:103], v[84:87], v[32:47]
	v_mfma_f32_32x32x16_bf16 v[48:63], v[116:119], v[84:87], v[48:63]
	s_waitcnt lgkmcnt(2)
	v_mfma_f32_32x32x16_bf16 v[32:47], v[104:107], v[88:91], v[32:47]
	v_mfma_f32_32x32x16_bf16 v[48:63], v[120:123], v[88:91], v[48:63]
	s_waitcnt lgkmcnt(0)
	v_mfma_f32_32x32x16_bf16 v[32:47], v[108:111], v[92:95], v[32:47]
	v_mfma_f32_32x32x16_bf16 v[48:63], v[124:127], v[92:95], v[48:63]
	v_add_u32_e32 v218, s100, v185
	ds_read_b64 v[64:65], v218 offset:8192
	ds_read_b64 v[66:67], v218 offset:8704
	ds_read_b64 v[68:69], v218 offset:9216
	ds_read_b64 v[70:71], v218 offset:9728
	ds_read_b64 v[72:73], v218 offset:10240
	ds_read_b64 v[74:75], v218 offset:10752
	ds_read_b64 v[76:77], v218 offset:11264
	ds_read_b64 v[78:79], v218 offset:11776
	ds_read_b64 v[138:139], v218 offset:12288
	ds_read_b64 v[140:141], v218 offset:12800
	ds_read_b64 v[142:143], v218 offset:13312
	ds_read_b64 v[144:145], v218 offset:13824
	ds_read_b64 v[146:147], v218 offset:14336
	ds_read_b64 v[148:149], v218 offset:14848
	ds_read_b64 v[150:151], v218 offset:15360
	ds_read_b64 v[152:153], v218 offset:15872
	s_cmp_ge_i32 s61, 50
	s_cbranch_scc1 .Lamoba_far
; #define NEGINF (-__builtin_inff())
; DI int crow(int i, int h) { return (i & 3) + 8 * (i >> 2) + 4 * h; }
; DI void moba_item(const Params& p, int b, int hd, int qb, const unsigned char* blut, const float* tbl) {
;     ...
;         int dist[16]; float bv[16];
; #pragma unroll
;         for (int i = 0; i < 16; ++i) dist[i] = t - (kt * 32 + crow(i, h));
;         bias16(blut, tblh, dist, bv);
; #pragma unroll
;         for (int i = 0; i < 16; ++i) lg[i] = (bs && dist[i] >= 0) ? s[i] + bv[i] : NEGINF;
	s_lshl_b32 s23, s61, 5
	v_add_u32_e32 v179, s23, v158
	v_lshl_add_u32 v182, v179, 2, v180
	v_subrev_u32_e32 v183, 128, v182
	ds_read_b32 v162, v182 offset:108
	ds_read_b32 v163, v182 offset:104
	ds_read_b32 v164, v182 offset:100
	ds_read_b32 v165, v182 offset:96
	ds_read_b32 v166, v182 offset:76
	ds_read_b32 v167, v182 offset:72
	ds_read_b32 v168, v182 offset:68
	ds_read_b32 v169, v182 offset:64
	ds_read_b32 v170, v182 offset:44
	ds_read_b32 v171, v182 offset:40
	ds_read_b32 v172, v182 offset:36
	ds_read_b32 v173, v182 offset:32
	ds_read_b32 v174, v182 offset:12
	ds_read_b32 v175, v182 offset:8
	ds_read_b32 v176, v182 offset:4
	ds_read_b32 v177, v182 offset:0
	s_waitcnt lgkmcnt(8)
	v_add_f32_e32 v32, v32, v162
	v_add_f32_e32 v33, v33, v163
	v_add_f32_e32 v34, v34, v164
	v_add_f32_e32 v35, v35, v165
	v_add_f32_e32 v36, v36, v166
	v_add_f32_e32 v37, v37, v167
	v_add_f32_e32 v38, v38, v168
	v_add_f32_e32 v39, v39, v169
	s_waitcnt lgkmcnt(0)
	v_add_f32_e32 v40, v40, v170
	v_add_f32_e32 v41, v41, v171
	v_add_f32_e32 v42, v42, v172
	v_add_f32_e32 v43, v43, v173
	v_add_f32_e32 v44, v44, v174
	v_add_f32_e32 v45, v45, v175
	v_add_f32_e32 v46, v46, v176
	v_add_f32_e32 v47, v47, v177
	ds_read_b32 v162, v183 offset:108
	ds_read_b32 v163, v183 offset:104
	ds_read_b32 v164, v183 offset:100
	ds_read_b32 v165, v183 offset:96
	ds_read_b32 v166, v183 offset:76
	ds_read_b32 v167, v183 offset:72
	ds_read_b32 v168, v183 offset:68
	ds_read_b32 v169, v183 offset:64
	ds_read_b32 v170, v183 offset:44
	ds_read_b32 v171, v183 offset:40
	ds_read_b32 v172, v183 offset:36
	ds_read_b32 v173, v183 offset:32
	ds_read_b32 v174, v183 offset:12
	ds_read_b32 v175, v183 offset:8
	ds_read_b32 v176, v183 offset:4
	ds_read_b32 v177, v183 offset:0
	s_waitcnt lgkmcnt(8)
	v_add_f32_e32 v48, v48, v162
	v_add_f32_e32 v49, v49, v163
	v_add_f32_e32 v50, v50, v164
	v_add_f32_e32 v51, v51, v165
	v_add_f32_e32 v52, v52, v166
	v_add_f32_e32 v53, v53, v167
	v_add_f32_e32 v54, v54, v168
	v_add_f32_e32 v55, v55, v169
	s_waitcnt lgkmcnt(0)
	v_add_f32_e32 v56, v56, v170
	v_add_f32_e32 v57, v57, v171
	v_add_f32_e32 v58, v58, v172
	v_add_f32_e32 v59, v59, v173
	v_add_f32_e32 v60, v60, v174
	v_add_f32_e32 v61, v61, v175
	v_add_f32_e32 v62, v62, v176
	v_add_f32_e32 v63, v63, v177
	s_cmp_ge_i32 s61, 2
	s_cbranch_scc1 .Lamoba_sm0
	v_subrev_u32_e32 v184, 32, v179
	v_cmp_le_i32_e32 vcc, 0, v179
	s_nop 1
	v_cndmask_b32_e32 v32, v199, v32, vcc
	v_cmp_le_i32_e32 vcc, 1, v179
	s_nop 1
	v_cndmask_b32_e32 v33, v199, v33, vcc
	v_cmp_le_i32_e32 vcc, 2, v179
	s_nop 1
	v_cndmask_b32_e32 v34, v199, v34, vcc
	v_cmp_le_i32_e32 vcc, 3, v179
	s_nop 1
	v_cndmask_b32_e32 v35, v199, v35, vcc
	v_cmp_le_i32_e32 vcc, 8, v179
	s_nop 1
	v_cndmask_b32_e32 v36, v199, v36, vcc
	v_cmp_le_i32_e32 vcc, 9, v179
	s_nop 1
	v_cndmask_b32_e32 v37, v199, v37, vcc
	v_cmp_le_i32_e32 vcc, 10, v179
	s_nop 1
	v_cndmask_b32_e32 v38, v199, v38, vcc
	v_cmp_le_i32_e32 vcc, 11, v179
	s_nop 1
	v_cndmask_b32_e32 v39, v199, v39, vcc
	v_cmp_le_i32_e32 vcc, 16, v179
	s_nop 1
	v_cndmask_b32_e32 v40, v199, v40, vcc
	v_cmp_le_i32_e32 vcc, 17, v179
	s_nop 1
	v_cndmask_b32_e32 v41, v199, v41, vcc
	v_cmp_le_i32_e32 vcc, 18, v179
	s_nop 1
	v_cndmask_b32_e32 v42, v199, v42, vcc
	v_cmp_le_i32_e32 vcc, 19, v179
	s_nop 1
	v_cndmask_b32_e32 v43, v199, v43, vcc
	v_cmp_le_i32_e32 vcc, 24, v179
	s_nop 1
	v_cndmask_b32_e32 v44, v199, v44, vcc
	v_cmp_le_i32_e32 vcc, 25, v179
	s_nop 1
	v_cndmask_b32_e32 v45, v199, v45, vcc
	v_cmp_le_i32_e32 vcc, 26, v179
	s_nop 1
	v_cndmask_b32_e32 v46, v199, v46, vcc
	v_cmp_le_i32_e32 vcc, 27, v179
	s_nop 1
	v_cndmask_b32_e32 v47, v199, v47, vcc
	v_cmp_le_i32_e32 vcc, 0, v184
	s_nop 1
	v_cndmask_b32_e32 v48, v199, v48, vcc
	v_cmp_le_i32_e32 vcc, 1, v184
	s_nop 1
	v_cndmask_b32_e32 v49, v199, v49, vcc
	v_cmp_le_i32_e32 vcc, 2, v184
	s_nop 1
	v_cndmask_b32_e32 v50, v199, v50, vcc
	v_cmp_le_i32_e32 vcc, 3, v184
	s_nop 1
	v_cndmask_b32_e32 v51, v199, v51, vcc
	v_cmp_le_i32_e32 vcc, 8, v184
	s_nop 1
	v_cndmask_b32_e32 v52, v199, v52, vcc
	v_cmp_le_i32_e32 vcc, 9, v184
	s_nop 1
	v_cndmask_b32_e32 v53, v199, v53, vcc
	v_cmp_le_i32_e32 vcc, 10, v184
	s_nop 1
	v_cndmask_b32_e32 v54, v199, v54, vcc
	v_cmp_le_i32_e32 vcc, 11, v184
	s_nop 1
	v_cndmask_b32_e32 v55, v199, v55, vcc
	v_cmp_le_i32_e32 vcc, 16, v184
	s_nop 1
	v_cndmask_b32_e32 v56, v199, v56, vcc
	v_cmp_le_i32_e32 vcc, 17, v184
	s_nop 1
	v_cndmask_b32_e32 v57, v199, v57, vcc
	v_cmp_le_i32_e32 vcc, 18, v184
	s_nop 1
	v_cndmask_b32_e32 v58, v199, v58, vcc
	v_cmp_le_i32_e32 vcc, 19, v184
	s_nop 1
	v_cndmask_b32_e32 v59, v199, v59, vcc
	v_cmp_le_i32_e32 vcc, 24, v184
	s_nop 1
	v_cndmask_b32_e32 v60, v199, v60, vcc
	v_cmp_le_i32_e32 vcc, 25, v184
	s_nop 1
	v_cndmask_b32_e32 v61, v199, v61, vcc
	v_cmp_le_i32_e32 vcc, 26, v184
	s_nop 1
	v_cndmask_b32_e32 v62, v199, v62, vcc
	v_cmp_le_i32_e32 vcc, 27, v184
	s_nop 1
	v_cndmask_b32_e32 v63, v199, v63, vcc
